# removed the now-unreachable inlined weight-convert loops replaced by the shared converter (no functional change)
# speedup vs baseline: 1.0003x; 1.0003x over previous
; #define LAS __attribute__((address_space(3)))
; __global__ void __launch_bounds__(NTHR, 2) mega_fwd(Params p) {
;     ...
;     if (IN(0)) {
;         convert_w((LAS float*)lds, p.w2, DFF, DM, W2, 0, 0, nullptr, G, bid);
;         convert_w((LAS float*)lds, p.w1, DM, DFF, W13, 1, 0, NG, G, bid);
;         convert_w((LAS float*)lds, p.w3, DM, DFF, W13, 1, 1, NG, G, bid);
.LBB0_22:
	s_andn2_b64 vcc, exec, s[6:7]
	v_lshrrev_b32_e32 v30, 4, v224
	s_branch .LBB0_44

; #define LAS __attribute__((address_space(3)))
; __global__ void __launch_bounds__(NTHR, 2) mega_fwd(Params p) {
;     ...
;     if (IN(2)) convert_w((LAS float*)lds, p.w_in, DM, 4096, WA, 0, 0, NG + 1 * DM, G, bid);
.Lcv_ret_3:
	s_branch .LBB0_238

; __device__ __forceinline__ void convert_w(LAS float* tile, const float* __restrict__ src, int K, int N, bf16_t* __restrict__ dst, int mode, int sidx, const float* __restrict__ gk, int G, int bid) {
;     const int tid = threadIdx.x;
;     const int tk = K / 64, tn = N / 64, ntile = tk * tn;
;     const int kk = tid >> 4, n4 = (tid & 15) * 4;
;     ...
;         const int n = tid >> 3, k8 = (tid & 7) * 8;
.Lcv_ret_4:
	v_lshlrev_b32_e32 v0, 2, v224
	v_lshrrev_b32_e32 v21, 4, v224
	s_cmpk_lt_i32 s79, 0
	v_and_b32_e32 v14, 60, v0
	v_lshlrev_b32_e32 v0, 3, v224
	v_mov_b32_e32 v15, 0
	v_and_b32_e32 v8, 56, v0
	v_lshrrev_b32_e32 v18, 3, v224
	v_mov_b32_e32 v9, v15
	v_mul_u32_u24_e32 v16, 0x104, v21
	v_mul_u32_u24_e32 v17, 0x104, v8
	s_branch .LBB0_385

; #define LAS __attribute__((address_space(3)))
; __global__ void __launch_bounds__(NTHR, 2) mega_fwd(Params p) {
;     ...
;         convert_w((LAS float*)lds, p.w2 + (size_t)1 * WSZ, DFF, DM, W2 + (size_t)DM * DFF, 0, 0, nullptr, G, bid);
;         convert_w((LAS float*)lds, p.w1 + (size_t)1 * WSZ, DM, DFF, W13 + (size_t)2 * DFF * DM, 1, 0, NG + 2 * DM, G, bid);
;         convert_w((LAS float*)lds, p.w3 + (size_t)1 * WSZ, DM, DFF, W13 + (size_t)2 * DFF * DM, 1, 1, NG + 2 * DM, G, bid);
.Lcv_site_p6:
	s_mov_b32 s98, 5
	s_branch .Lcv_entry

; #define LAS __attribute__((address_space(3)))
; #define SEAM(k) do { if (IN(k) && IN((k) + 1)) xcd_barrier(xbar); } while (0)
; __global__ void __launch_bounds__(NTHR, 2) mega_fwd(Params p) {
;     ...
;         convert_w((LAS float*)lds, p.w3 + (size_t)1 * WSZ, DM, DFF, W13 + (size_t)2 * DFF * DM, 1, 1, NG + 2 * DM, G, bid);
;     }
;     SEAM(6);
;     if (IN(7)) { Gemm g{HB, W13 + (size_t)2 * DFF * DM, DM, DM, SEQ, 2 * DFF, DM, 0}; StaticOrder S; S.init(SEQ, 2 * DFF, G, bid); EpiSwiglu E{BIG, DFF, RS + 2 * SEQ}; gemm_phase(lds, g, S, E); }
.Lcv_ret_7:
	s_mov_b64 s[0:1], -1

; #define LAS __attribute__((address_space(3)))
; __global__ void __launch_bounds__(NTHR, 2) mega_fwd(Params p) {
;     ...
;         convert_w((LAS float*)lds, p.w2 + (size_t)2 * WSZ, DFF, DM, W2, 0, 0, nullptr, G, bid);
;         convert_w((LAS float*)lds, p.w1 + (size_t)2 * WSZ, DM, DFF, W13, 1, 0, NG + 3 * DM, G, bid);
;         convert_w((LAS float*)lds, p.w3 + (size_t)2 * WSZ, DM, DFF, W13, 1, 1, NG + 3 * DM, G, bid);
.Lcv_site_p8:
	s_mov_b32 s98, 8
	s_branch .Lcv_entry

; #define LAS __attribute__((address_space(3)))
; __global__ void __launch_bounds__(NTHR, 2) mega_fwd(Params p) {
;     ...
;         convert_w((LAS float*)lds, p.w2 + (size_t)3 * WSZ, DFF, DM, W2 + (size_t)DM * DFF, 0, 0, nullptr, G, bid);
;         convert_w((LAS float*)lds, p.w1 + (size_t)3 * WSZ, DM, DFF, W13 + (size_t)2 * DFF * DM, 1, 0, NG + 5 * DM, G, bid);
;         convert_w((LAS float*)lds, p.w3 + (size_t)3 * WSZ, DM, DFF, W13 + (size_t)2 * DFF * DM, 1, 1, NG + 5 * DM, G, bid);
.Lcv_site_p15:
	s_mov_b32 s98, 13
	s_branch .Lcv_entry
